# FoX QK^T: chunk-2/3 K-fragment reads kept in flight through a third register quad instead of lgkmcnt(0) right before use
# baseline (speedup 1.0000x reference)
; #define LAS __attribute__((address_space(3)))
; DI int crow(int r, int hi) { return (r & 3) + 8 * (r >> 2) + 4 * hi; }
; #define MFMA32(a, b, c) __builtin_amdgcn_mfma_f32_32x32x16_bf16((a), (b), (c), 0, 0, 0)
; template <int MODE> DI void attn_unit(int b, int qb, const bf16* Qb, int qpitch, const bf16* Kb, int kpitch, const bf16* VT, bf16* O, float* ssq, ...
;     ...
;         if (active) {
;             const LAS unsigned char* kb = lds + KOFF + buf * KSZ + r32 * PK + 16 * hi;
;             v16f p0, p1;
; #pragma unroll
;             for (int d0 = 0; d0 < ND; ++d0) {
;                 const v8s ka = *(const LAS v8s*)(kb + 32 * d0), kb2 = *(const LAS v8s*)(kb + 32 * PK + 32 * d0);
;                 if (d0 == 0) { p0 = MFMA32(ka, qr[0], (v16f){}); p1 = MFMA32(kb2, qr[0], (v16f){}); }
;                 else { p0 = MFMA32(ka, qr[d0], p0); p1 = MFMA32(kb2, qr[d0], p1); }
;             }
;             asm volatile("s_nop 15\n\ts_nop 7" : "+v"(p0), "+v"(p1));
;             if (MODE == 1) {
;                 const LAS float* fb = (const LAS float*)(lds + FOFF + buf * 256);
; #pragma unroll
;                 for (int g = 0; g < 4; ++g) {
;                     const v4f f0 = *(const LAS v4f*)(fb + 8 * g + 4 * hi), f1 = *(const LAS v4f*)(fb + 32 + 8 * g + 4 * hi);
; #pragma unroll
;                     for (int i = 0; i < 4; ++i) { p0[4 * g + i] += f0[i]; p1[4 * g + i] += f1[i]; }
;                 }
;             }
;             if (MODE == 0) {
;                 const LAS float* tb = MS + (223 - q + k0 + 4 * hi);
; #pragma unroll
;                 for (int r = 0; r < 16; ++r) { p0[r] += tb[(r & 3) + 8 * (r >> 2)]; p1[r] += tb[32 + (r & 3) + 8 * (r >> 2)]; }
;             } else if (k0 + 63 > qw0) {
; #pragma unroll
;                 for (int r = 0; r < 16; ++r) {
;                     const int kv = k0 + crow(r, hi);
;                     if (kv > q) p0[r] = NEGBIG;
;                     if (kv + 32 > q) p1[r] = NEGBIG;
;                 }
.LBB0_509:
	s_mul_i32 s24, s72, 0x2400
	v_add_u32_e32 v172, s24, v199
	ds_read_b128 v[32:35], v172 offset:4608
	ds_read_b128 v[36:39], v172
	ds_read_b128 v[182:185], v172 offset:32
	ds_read_b128 v[186:189], v172 offset:4640
	ds_read_b128 v[236:239], v172 offset:4672
	s_add_i32 s24, s59, 0xff
	s_cmp_le_i32 s24, s15
	s_waitcnt lgkmcnt(3)
	v_mfma_f32_32x32x16_bf16 v[48:63], v[36:39], v[66:69], 0
	v_mfma_f32_32x32x16_bf16 v[32:47], v[32:35], v[66:69], 0
	s_waitcnt lgkmcnt(2)
	v_mfma_f32_32x32x16_bf16 v[48:63], v[182:185], v[70:73], v[48:63]
	ds_read_b128 v[182:185], v172 offset:64
	s_waitcnt lgkmcnt(2)
	v_mfma_f32_32x32x16_bf16 v[32:47], v[186:189], v[70:73], v[32:47]
	ds_read_b128 v[186:189], v172 offset:4704
	s_waitcnt lgkmcnt(1)
	v_mfma_f32_32x32x16_bf16 v[48:63], v[182:185], v[74:77], v[48:63]
	ds_read_b128 v[182:185], v172 offset:96
	v_mfma_f32_32x32x16_bf16 v[32:47], v[236:239], v[74:77], v[32:47]
	v_lshl_add_u32 v172, s72, 8, v202
	s_waitcnt lgkmcnt(1)
	v_mfma_f32_32x32x16_bf16 v[32:47], v[186:189], v[78:81], v[32:47]
	s_waitcnt lgkmcnt(0)
	v_mfma_f32_32x32x16_bf16 v[48:63], v[182:185], v[78:81], v[48:63]
	ds_read_b128 v[182:185], v172 offset:35840
	ds_read_b128 v[218:221], v172 offset:35872
	ds_read_b128 v[222:225], v172 offset:35968
	ds_read_b128 v[242:245], v172 offset:36000
	s_nop 7
	s_waitcnt lgkmcnt(3)
	v_pk_add_f32 v[188:189], v[182:183], v[48:49]
	v_pk_add_f32 v[186:187], v[184:185], v[50:51]
	s_waitcnt lgkmcnt(2)
	v_pk_add_f32 v[184:185], v[52:53], v[218:219]
	v_pk_add_f32 v[182:183], v[54:55], v[220:221]
	ds_read_b128 v[48:51], v172 offset:35904
	ds_read_b128 v[218:221], v172 offset:36032
	s_waitcnt lgkmcnt(2)
	v_pk_add_f32 v[38:39], v[38:39], v[244:245]
	v_pk_add_f32 v[34:35], v[34:35], v[224:225]
	v_pk_add_f32 v[32:33], v[32:33], v[222:223]
	s_waitcnt lgkmcnt(1)
	v_pk_add_f32 v[54:55], v[56:57], v[48:49]
	v_pk_add_f32 v[48:49], v[58:59], v[50:51]
	ds_read_b128 v[56:59], v172 offset:35936
	ds_read_b128 v[246:249], v172 offset:36064
	s_waitcnt lgkmcnt(1)
	v_pk_add_f32 v[52:53], v[60:61], v[56:57]
	v_pk_add_f32 v[50:51], v[62:63], v[58:59]
	s_waitcnt lgkmcnt(0)
	v_pk_add_f32 v[44:45], v[44:45], v[246:247]
	v_pk_add_f32 v[56:57], v[40:41], v[218:219]
	v_pk_add_f32 v[58:59], v[36:37], v[242:243]
	v_pk_add_f32 v[36:37], v[46:47], v[248:249]
	v_pk_add_f32 v[40:41], v[42:43], v[220:221]
	s_cbranch_scc1 .LBB0_511
	v_add_u32_e32 v42, s59, v194
	v_add_u32_e32 v46, 0xe0, v42
	v_add_u32_e32 v43, 0xc0, v42
	v_cmp_le_i32_e32 vcc, v46, v168
	s_nop 1
	v_cndmask_b32_e32 v32, v234, v32, vcc
	v_cmp_le_i32_e32 vcc, v43, v168
	s_nop 1
	v_cndmask_b32_e32 v188, v234, v188, vcc
	v_cmp_lt_i32_e32 vcc, v43, v168
	v_add_u32_e32 v43, 0xe1, v42
	s_nop 0
	v_cndmask_b32_e32 v189, v234, v189, vcc
	v_cmp_le_i32_e32 vcc, v43, v168
	v_add_u32_e32 v43, 0xc2, v42
	s_nop 0
	v_cndmask_b32_e32 v33, v234, v33, vcc
	v_cmp_le_i32_e32 vcc, v43, v168
	v_add_u32_e32 v43, 0xe2, v42
	s_nop 0
	v_cndmask_b32_e32 v186, v234, v186, vcc
	v_cmp_le_i32_e32 vcc, v43, v168
	v_add_u32_e32 v43, 0xc3, v42
	s_nop 0
	v_cndmask_b32_e32 v34, v234, v34, vcc
	v_cmp_le_i32_e32 vcc, v43, v168
	v_add_u32_e32 v43, 0xe3, v42
	s_nop 0
	v_cndmask_b32_e32 v187, v234, v187, vcc
	v_cmp_le_i32_e32 vcc, v43, v168
	v_add_u32_e32 v43, 0xc8, v42
	s_nop 0
	v_cndmask_b32_e32 v35, v234, v35, vcc
	v_cmp_le_i32_e32 vcc, v43, v168
	v_add_u32_e32 v43, 0xe8, v42
	s_nop 0
	v_cndmask_b32_e32 v184, v234, v184, vcc
	v_cmp_le_i32_e32 vcc, v43, v168
	v_add_u32_e32 v43, 0xc9, v42
	s_nop 0
	v_cndmask_b32_e32 v58, v234, v58, vcc
	v_cmp_le_i32_e32 vcc, v43, v168
	v_add_u32_e32 v43, 0xe9, v42
	s_nop 0
	v_cndmask_b32_e32 v185, v234, v185, vcc
	v_cmp_le_i32_e32 vcc, v43, v168
	v_add_u32_e32 v43, 0xca, v42
	s_nop 0
	v_cndmask_b32_e32 v59, v234, v59, vcc
	v_cmp_le_i32_e32 vcc, v43, v168
	v_add_u32_e32 v43, 0xea, v42
	s_nop 0
	v_cndmask_b32_e32 v182, v234, v182, vcc
	v_cmp_le_i32_e32 vcc, v43, v168
	v_add_u32_e32 v43, 0xcb, v42
	s_nop 0
	v_cndmask_b32_e32 v38, v234, v38, vcc
	v_cmp_le_i32_e32 vcc, v43, v168
	v_add_u32_e32 v43, 0xeb, v42
	s_nop 0
	v_cndmask_b32_e32 v183, v234, v183, vcc
	v_cmp_le_i32_e32 vcc, v43, v168
	v_add_u32_e32 v43, 0xd0, v42
	s_nop 0
	v_cndmask_b32_e32 v39, v234, v39, vcc
	v_cmp_le_i32_e32 vcc, v43, v168
	v_add_u32_e32 v43, 0xf0, v42
	s_nop 0
	v_cndmask_b32_e32 v54, v234, v54, vcc
	v_cmp_le_i32_e32 vcc, v43, v168
	v_add_u32_e32 v43, 0xd1, v42
	s_nop 0
	v_cndmask_b32_e32 v56, v234, v56, vcc
	v_cmp_le_i32_e32 vcc, v43, v168
	v_add_u32_e32 v43, 0xf1, v42
	s_nop 0
	v_cndmask_b32_e32 v55, v234, v55, vcc
	v_cmp_le_i32_e32 vcc, v43, v168
	v_add_u32_e32 v43, 0xd2, v42
	s_nop 0
	v_cndmask_b32_e32 v57, v234, v57, vcc
	v_cmp_le_i32_e32 vcc, v43, v168
	v_add_u32_e32 v43, 0xf2, v42
	s_nop 0
	v_cndmask_b32_e32 v48, v234, v48, vcc
	v_cmp_le_i32_e32 vcc, v43, v168
	v_add_u32_e32 v43, 0xd3, v42
	s_nop 0
	v_cndmask_b32_e32 v40, v234, v40, vcc
	v_cmp_le_i32_e32 vcc, v43, v168
	v_add_u32_e32 v43, 0xf3, v42
	s_nop 0
	v_cndmask_b32_e32 v49, v234, v49, vcc
	v_cmp_le_i32_e32 vcc, v43, v168
	v_add_u32_e32 v43, 0xd8, v42
	s_nop 0
	v_cndmask_b32_e32 v41, v234, v41, vcc
	v_cmp_le_i32_e32 vcc, v43, v168
	v_add_u32_e32 v43, 0xf8, v42
	s_nop 0
	v_cndmask_b32_e32 v52, v234, v52, vcc
	v_cmp_le_i32_e32 vcc, v43, v168
	v_add_u32_e32 v43, 0xd9, v42
	s_nop 0
	v_cndmask_b32_e32 v44, v234, v44, vcc
	v_cmp_le_i32_e32 vcc, v43, v168
	v_add_u32_e32 v43, 0xf9, v42
	s_nop 0
	v_cndmask_b32_e32 v53, v234, v53, vcc
	v_cmp_le_i32_e32 vcc, v43, v168
	v_add_u32_e32 v43, 0xda, v42
	s_nop 0
	v_cndmask_b32_e32 v45, v234, v45, vcc
	v_cmp_le_i32_e32 vcc, v43, v168
	v_add_u32_e32 v43, 0xfa, v42
	s_nop 0
	v_cndmask_b32_e32 v50, v234, v50, vcc
	v_cmp_le_i32_e32 vcc, v43, v168
	v_add_u32_e32 v43, 0xdb, v42
	v_add_u32_e32 v42, 0xfb, v42
	v_cndmask_b32_e32 v36, v234, v36, vcc
	v_cmp_le_i32_e32 vcc, v43, v168
	s_nop 1
	v_cndmask_b32_e32 v51, v234, v51, vcc
	v_cmp_le_i32_e32 vcc, v42, v168
	s_nop 1
	v_cndmask_b32_e32 v37, v234, v37, vcc
